# g3: defer gate-value shifts/waits to first use, on top of gw hoist + scan rebalance + priorities + wide stores + read split
# baseline (speedup 1.0000x reference)
; DI void gla_g3_block(const P& p, int cgi, int hh, char* smem) {
;     ...
;   const int row8 = tid >> 3, kc = tid & 7;
;   const bf16_t* outb = (const bf16_t*)p.out;
;   u4 ld[10];
;   {
;     const long qoff = (long)(t0 + row8) * 256 + hh * 64 + kc * 8;
;     ld[0] = *(const u4*)((const bf16_t*)((const char*)outb + OUT_QEF) + qoff);
;     ld[1] = *(const u4*)((const bf16_t*)((const char*)outb + OUT_KEF) + qoff);
;     ld[4] = *(const u4*)((const bf16_t*)((const char*)outb + OUT_QEB) + qoff);
;     ld[5] = *(const u4*)((const bf16_t*)((const char*)outb + OUT_KEB) + qoff);
;     const bf16_t* S0 = (const bf16_t*)(p.ws + OFF_UBUF) + (long)((cgi * 4 + hh) * 2) * 8192 + row8 * 64 + kc * 8;
;     ld[2] = *(const u4*)(S0);
;     ld[3] = *(const u4*)(S0 + 64 * 64);
;     ld[6] = *(const u4*)(S0 + 8192);
;     ld[7] = *(const u4*)(S0 + 8192 + 64 * 64);
;     const bf16_t* gvt = (const bf16_t*)(p.ws + OFF_GV) + (long)(hh * 128 + row8) * T + t0 + kc * 8;
;     ld[8] = *(const u4*)(gvt);
;     ld[9] = *(const u4*)(gvt + (long)64 * T);
;   }
;   __syncthreads();
;   {
;     const int so = row8 * GROW + kc * 16;
;     *(u4*)(smem + O_QE + so) = ld[0];
;     *(u4*)(smem + O_KE + so) = ld[1];
;     *(u4*)(smem + O_S + so) = ld[2];
;     *(u4*)(smem + O_S + 64 * GROW + so) = ld[3];
;     *(u4*)(smem + DIRB + O_QE + so) = ld[4];
;     *(u4*)(smem + DIRB + O_KE + so) = ld[5];
;     *(u4*)(smem + DIRB + O_S + so) = ld[6];
;     *(u4*)(smem + DIRB + O_S + 64 * GROW + so) = ld[7];
;     *(u4*)(smem + O_VT + so) = ld[8];
;     *(u4*)(smem + O_VT + 64 * GROW + so) = ld[9];
;   }
;   __syncthreads();
;   unsigned graw[8][4];
;   if (dir == 0) {
;     const bf16_t* og = (const bf16_t*)(p.ws + OFF_OG);
; #pragma unroll
;     for (int j = 0; j < 8; ++j)
; #pragma unroll
;       for (int r = 0; r < 4; ++r) graw[j][r] = og[(long)(t0 + 16 * slab + 4 * q4 + r) * 512 + hh * 128 + 16 * j + r16];
;   }
.LBB0_569:
	s_ashr_i32 s4, s56, 2
	s_and_b32 s6, s56, 3
	s_lshl_b32 s50, s4, 6
	s_lshl_b32 s4, s4, 3
	s_lshl_b32 s5, s6, 1
	s_or_b32 s4, s5, s4
	s_ashr_i32 s5, s4, 31
	s_lshl_b64 s[4:5], s[4:5], 14
	v_add_u32_e32 v0, s50, v33
	v_lshl_add_u64 v[24:25], v[40:41], 0, s[4:5]
	v_ashrrev_i32_e32 v1, 31, v0
	v_add_co_u32_e32 v20, vcc, s47, v24
	v_lshlrev_b64 v[0:1], 8, v[0:1]
	s_nop 0
	v_addc_co_u32_e32 v21, vcc, 0, v25, vcc
	v_lshl_or_b32 v0, s6, 6, v0
	v_add_co_u32_e32 v26, vcc, s49, v24
	v_or_b32_e32 v0, v0, v36
	s_nop 0
	v_addc_co_u32_e32 v27, vcc, 0, v25, vcc
	s_lshl_b32 s57, s6, 7
	v_lshlrev_b64 v[12:13], 1, v[0:1]
	v_add_co_u32_e32 v28, vcc, s52, v24
	v_or_b32_e32 v34, s57, v33
	v_lshl_add_u64 v[0:1], s[34:35], 0, v[12:13]
	v_lshl_add_u64 v[4:5], s[36:37], 0, v[12:13]
	v_lshl_add_u64 v[8:9], s[38:39], 0, v[12:13]
	v_lshl_add_u64 v[12:13], s[40:41], 0, v[12:13]
	v_addc_co_u32_e32 v29, vcc, 0, v25, vcc
	v_mul_u32_u24_e32 v34, 0x14000, v34
	global_load_dwordx4 v[0:3], v[0:1], off
	s_nop 0
	global_load_dwordx4 v[4:7], v[4:5], off
	s_nop 0
	global_load_dwordx4 v[8:11], v[8:9], off
	v_lshlrev_b32_e32 v34, 1, v34
	global_load_dwordx4 v[12:15], v[12:13], off
	s_nop 0
	global_load_dwordx4 v[16:19], v[24:25], off
	s_nop 0
	global_load_dwordx4 v[20:23], v[20:21], off
	s_nop 0
	global_load_dwordx4 v[24:27], v[26:27], off
	s_nop 0
	global_load_dwordx4 v[28:31], v[28:29], off
	v_lshl_add_u64 v[50:51], s[42:43], 0, v[34:35]
	s_ashr_i32 s51, s50, 31
	v_lshl_add_u64 v[50:51], s[50:51], 1, v[50:51]
	v_lshl_add_u64 v[54:55], v[50:51], 0, v[48:49]
	global_load_dwordx4 v[50:53], v[54:55], off
	v_add_co_u32_e32 v54, vcc, s53, v54
	v_readfirstlane_b32 s4, v210
	s_nop 0
	v_addc_co_u32_e32 v55, vcc, 0, v55, vcc
	global_load_dwordx4 v[54:57], v[54:55], off
	s_cmpk_lt_u32 s4, 0x100
	s_cselect_b64 vcc, -1, 0
	s_lshr_b32 s5, s4, 2
	s_and_b32 s6, s5, 0x3ffffff0
	v_mov_b32_e32 v83, 0
	v_mov_b32_e32 v84, 0
	v_mov_b32_e32 v87, 0
	v_mov_b32_e32 v88, 0
	v_mov_b32_e32 v89, 0
	v_mov_b32_e32 v90, 0
	v_mov_b32_e32 v91, 0
	v_mov_b32_e32 v92, 0
	v_mov_b32_e32 v93, 0
	v_mov_b32_e32 v94, 0
	v_mov_b32_e32 v95, 0
	v_mov_b32_e32 v96, 0
	v_mov_b32_e32 v97, 0
	v_mov_b32_e32 v98, 0
	v_mov_b32_e32 v99, 0
	s_cmpk_gt_u32 s4, 0xff
	v_mov_b32_e32 v100, 0
	v_mov_b32_e32 v101, 0
	v_mov_b32_e32 v102, 0
	v_mov_b32_e32 v103, 0
	v_mov_b32_e32 v104, 0
	v_mov_b32_e32 v105, 0
	v_mov_b32_e32 v106, 0
	v_mov_b32_e32 v107, 0
	v_mov_b32_e32 v108, 0
	v_mov_b32_e32 v109, 0
	v_mov_b32_e32 v110, 0
	v_mov_b32_e32 v86, 0
	v_mov_b32_e32 v85, 0
	v_mov_b32_e32 v82, 0
	v_mov_b32_e32 v81, 0
	v_mov_b32_e32 v80, 0
	v_mov_b32_e32 v34, 0
	s_waitcnt lgkmcnt(0)
	s_barrier
	s_waitcnt vmcnt(5)
	ds_write_b128 v68, v[16:19] offset:18432
	s_waitcnt vmcnt(4)
	ds_write_b128 v68, v[20:23] offset:27648
	s_waitcnt vmcnt(3)
	ds_write_b128 v68, v[24:27] offset:55296
	s_waitcnt vmcnt(2)
	ds_write_b128 v68, v[28:31] offset:64512
	s_waitcnt vmcnt(1)
	ds_write_b128 v77, v[50:53]
	ds_write_b128 v68, v[0:3]
	ds_write_b128 v68, v[4:7] offset:9216
	ds_write_b128 v68, v[8:11] offset:36864
	ds_write_b128 v68, v[12:15] offset:46080
	s_waitcnt vmcnt(0)
	ds_write_b128 v78, v[54:57]
	s_waitcnt lgkmcnt(0)
	s_barrier
	s_cbranch_scc1 .LBB0_571
	v_or_b32_e32 v0, s50, v37
	v_or_b32_e32 v0, s6, v0
	v_ashrrev_i32_e32 v1, 31, v0
	v_lshlrev_b64 v[4:5], 10, v[0:1]
	v_or_b32_e32 v6, 1, v0
	v_or_b32_e32 v8, 2, v0
	v_or_b32_e32 v0, 3, v0
	s_lshl_b32 s44, s57, 1
	v_ashrrev_i32_e32 v7, 31, v6
	v_ashrrev_i32_e32 v1, 31, v0
	v_lshl_add_u64 v[2:3], v[42:43], 0, s[44:45]
	v_lshlrev_b64 v[6:7], 10, v[6:7]
	v_ashrrev_i32_e32 v9, 31, v8
	v_lshlrev_b64 v[0:1], 10, v[0:1]
	v_lshl_add_u64 v[4:5], v[2:3], 0, v[4:5]
	v_lshl_add_u64 v[6:7], v[2:3], 0, v[6:7]
	v_lshlrev_b64 v[8:9], 10, v[8:9]
	v_lshl_add_u64 v[0:1], v[2:3], 0, v[0:1]
	v_lshl_add_u64 v[8:9], v[2:3], 0, v[8:9]
	global_load_ushort v173, v[4:5], off
	global_load_ushort v174, v[4:5], off offset:32
	global_load_ushort v175, v[4:5], off offset:64
	global_load_ushort v176, v[4:5], off offset:96
	global_load_ushort v177, v[4:5], off offset:128
	global_load_ushort v178, v[4:5], off offset:160
	global_load_ushort v179, v[4:5], off offset:192
	s_nop 0
	global_load_ushort v180, v[4:5], off offset:224
	s_nop 0
	global_load_ushort v181, v[6:7], off
	global_load_ushort v182, v[0:1], off
	global_load_ushort v183, v[8:9], off
	global_load_ushort v184, v[6:7], off offset:32
	global_load_ushort v185, v[0:1], off offset:32
	global_load_ushort v186, v[8:9], off offset:32
	global_load_ushort v187, v[6:7], off offset:64
	global_load_ushort v188, v[0:1], off offset:64
	global_load_ushort v189, v[8:9], off offset:64
	global_load_ushort v190, v[6:7], off offset:96
	global_load_ushort v191, v[0:1], off offset:96
	global_load_ushort v192, v[8:9], off offset:96
	global_load_ushort v193, v[6:7], off offset:128
	global_load_ushort v194, v[0:1], off offset:128
	global_load_ushort v195, v[8:9], off offset:128
	global_load_ushort v196, v[6:7], off offset:160
	global_load_ushort v197, v[0:1], off offset:160
	global_load_ushort v198, v[8:9], off offset:160
	global_load_ushort v199, v[6:7], off offset:192
	global_load_ushort v228, v[8:9], off offset:192
	global_load_ushort v229, v[0:1], off offset:192
	s_nop 0
	global_load_ushort v230, v[6:7], off offset:224
	s_nop 0
	global_load_ushort v231, v[8:9], off offset:224
	s_nop 0
	global_load_ushort v232, v[0:1], off offset:224

; DI void gla_g3_block(const P& p, int cgi, int hh, char* smem) {
;     ...
;   if (dir == 0) {
; #pragma unroll
;     for (int j = 0; j < 8; ++j)
; #pragma unroll
;       for (int r = 0; r < 4; ++r) o[j][r] += ob[(16 * slab + 4 * q4 + r) * 132 + 16 * j + r16];
;     float ss[4];
; #pragma unroll
;     for (int r = 0; r < 4; ++r) {
;       float sq = 0.f;
; #pragma unroll
;       for (int j = 0; j < 8; ++j) sq += o[j][r] * o[j][r];
;       sq += __shfl_xor(sq, 1); sq += __shfl_xor(sq, 2); sq += __shfl_xor(sq, 4); sq += __shfl_xor(sq, 8);
;       ss[r] = rsqrtf(sq * (1.f / 128.f) + EPS);
.LBB0_573:
	s_andn2_b64 vcc, exec, vcc
	s_waitcnt lgkmcnt(0)
	s_barrier
	s_cbranch_vccnz .LBB0_568
	v_or_b32_e32 v140, s6, v37
	v_mad_u64_u32 v[50:51], s[4:5], v140, s54, v[38:39]
	ds_read2_b32 v[112:113], v50 offset1:16
	ds_read2_b32 v[114:115], v50 offset0:132 offset1:148
	v_add_u32_e32 v51, 0x400, v50
	ds_read2_b32 v[116:117], v51 offset0:8 offset1:24
	ds_read2_b32 v[118:119], v51 offset0:140 offset1:156
	ds_read2_b32 v[52:53], v50 offset0:32 offset1:48
	ds_read2_b32 v[56:57], v50 offset0:164 offset1:180
	ds_read2_b32 v[120:121], v51 offset0:40 offset1:56
	ds_read2_b32 v[122:123], v51 offset0:172 offset1:188
	ds_read2_b32 v[124:125], v50 offset0:64 offset1:80
	ds_read2_b32 v[126:127], v50 offset0:196 offset1:212
	ds_read2_b32 v[128:129], v51 offset0:72 offset1:88
	ds_read2_b32 v[58:59], v51 offset0:204 offset1:220
	ds_read2_b32 v[130:131], v50 offset0:96 offset1:112
	ds_read2_b32 v[132:133], v50 offset0:228 offset1:244
	ds_read2_b32 v[134:135], v51 offset0:104 offset1:120
	ds_read2_b32 v[60:61], v51 offset0:236 offset1:252
	v_and_b32_e32 v51, 64, v79
	v_xor_b32_e32 v50, 1, v79
	v_add_u32_e32 v111, 64, v51
	v_cmp_lt_i32_e32 vcc, v50, v111
	v_mov_b32_e32 v51, v28
	v_mov_b32_e32 v28, v25
	v_cndmask_b32_e32 v50, v79, v50, vcc
	v_lshlrev_b32_e32 v141, 2, v50
	v_mov_b32_e32 v50, v24
	s_waitcnt lgkmcnt(10)
	v_pk_add_f32 v[24:25], v[28:29], v[56:57]
	v_mov_b32_e32 v28, v112
	v_mov_b32_e32 v29, v114
	v_mov_b32_e32 v114, v113
	v_pk_add_f32 v[54:55], v[50:51], v[52:53]
	v_pk_add_f32 v[56:57], v[16:17], v[28:29]
	v_pk_add_f32 v[28:29], v[12:13], v[114:115]
	v_pk_mul_f32 v[136:137], v[54:55], v[54:55]
	v_mov_b32_e32 v50, v20
	v_mov_b32_e32 v51, v4
	v_pk_mul_f32 v[138:139], v[24:25], v[24:25]
	v_pk_mul_f32 v[12:13], v[28:29], v[28:29]
	v_mov_b32_e32 v4, v21
	s_waitcnt lgkmcnt(7)
	v_pk_add_f32 v[52:53], v[50:51], v[124:125]
	v_pk_fma_f32 v[16:17], v[56:57], v[56:57], v[12:13]
	s_waitcnt lgkmcnt(6)
	v_pk_add_f32 v[12:13], v[4:5], v[126:127]
	v_mov_b32_e32 v20, v138
	v_mov_b32_e32 v21, v136
	v_pk_mul_f32 v[124:125], v[52:53], v[52:53]
	v_mov_b32_e32 v50, v8
	v_mov_b32_e32 v51, v0
	v_pk_mul_f32 v[4:5], v[12:13], v[12:13]
	v_mov_b32_e32 v0, v9
	v_pk_add_f32 v[16:17], v[16:17], v[20:21] op_sel:[1,0] op_sel_hi:[0,1]
	v_mov_b32_e32 v136, v139
	s_waitcnt lgkmcnt(3)
	v_pk_add_f32 v[50:51], v[50:51], v[130:131]
	s_waitcnt lgkmcnt(2)
	v_pk_add_f32 v[0:1], v[0:1], v[132:133]
	v_pk_add_f32 v[16:17], v[16:17], v[136:137]
	v_mov_b32_e32 v20, v4
	v_mov_b32_e32 v21, v124
	v_pk_mul_f32 v[130:131], v[50:51], v[50:51]
	v_pk_mul_f32 v[8:9], v[0:1], v[0:1]
	v_pk_add_f32 v[16:17], v[16:17], v[20:21]
	v_mov_b32_e32 v124, v5
	v_pk_add_f32 v[4:5], v[16:17], v[124:125]
	v_mov_b32_e32 v16, v8
	v_mov_b32_e32 v17, v130
	v_pk_add_f32 v[4:5], v[4:5], v[16:17]
	v_mov_b32_e32 v130, v9
	v_pk_add_f32 v[4:5], v[4:5], v[130:131]
	ds_bpermute_b32 v9, v141, v5
	ds_bpermute_b32 v8, v141, v4
	v_mov_b32_e32 v113, v165
	v_xor_b32_e32 v16, 2, v79
	v_cmp_lt_i32_e32 vcc, v16, v111
	s_lshl_b32 s44, s57, 1
	s_waitcnt lgkmcnt(0)
	v_pk_add_f32 v[4:5], v[4:5], v[8:9]
	v_cndmask_b32_e32 v16, v79, v16, vcc
	v_lshlrev_b32_e32 v112, 2, v16
	ds_bpermute_b32 v9, v112, v5
	ds_bpermute_b32 v8, v112, v4
	v_xor_b32_e32 v16, 4, v79
	v_cmp_lt_i32_e32 vcc, v16, v111
	s_waitcnt lgkmcnt(0)
	v_pk_add_f32 v[4:5], v[4:5], v[8:9]
	v_cndmask_b32_e32 v16, v79, v16, vcc
	v_lshlrev_b32_e32 v130, 2, v16
	ds_bpermute_b32 v9, v130, v5
	ds_bpermute_b32 v8, v130, v4
	v_xor_b32_e32 v16, 8, v79
	v_cmp_lt_i32_e32 vcc, v16, v111
	s_waitcnt lgkmcnt(0)
	v_pk_add_f32 v[114:115], v[4:5], v[8:9]
	v_mov_b32_e32 v5, v30
	v_mov_b32_e32 v30, v27
	v_cndmask_b32_e32 v16, v79, v16, vcc
	v_mov_b32_e32 v4, v26
	v_pk_add_f32 v[20:21], v[30:31], v[122:123]
	v_mov_b32_e32 v31, v118
	v_mov_b32_e32 v118, v117
	v_lshlrev_b32_e32 v111, 2, v16
	v_pk_add_f32 v[16:17], v[4:5], v[120:121]
	v_mov_b32_e32 v30, v116
	v_pk_add_f32 v[14:15], v[14:15], v[118:119]
	v_pk_mul_f32 v[120:121], v[16:17], v[16:17]
	v_mov_b32_e32 v4, v22
	v_mov_b32_e32 v5, v6
	v_pk_mul_f32 v[26:27], v[20:21], v[20:21]
	v_pk_add_f32 v[18:19], v[18:19], v[30:31]
	v_pk_mul_f32 v[30:31], v[14:15], v[14:15]
	v_mov_b32_e32 v6, v23
	v_pk_add_f32 v[8:9], v[4:5], v[128:129]
	v_pk_fma_f32 v[30:31], v[18:19], v[18:19], v[30:31]
	v_pk_add_f32 v[6:7], v[6:7], v[58:59]
	v_mov_b32_e32 v58, v26
	v_mov_b32_e32 v59, v120
	v_pk_mul_f32 v[126:127], v[8:9], v[8:9]
	v_mov_b32_e32 v4, v10
	v_mov_b32_e32 v5, v2
	v_pk_mul_f32 v[22:23], v[6:7], v[6:7]
	v_mov_b32_e32 v2, v11
	v_pk_add_f32 v[30:31], v[30:31], v[58:59] op_sel:[1,0] op_sel_hi:[0,1]
	v_mov_b32_e32 v120, v27
	v_pk_add_f32 v[4:5], v[4:5], v[134:135]
	v_pk_add_f32 v[2:3], v[2:3], v[60:61]
	v_pk_add_f32 v[26:27], v[30:31], v[120:121]
	v_mov_b32_e32 v30, v22
	v_mov_b32_e32 v31, v126
	v_pk_mul_f32 v[128:129], v[4:5], v[4:5]
	v_pk_mul_f32 v[10:11], v[2:3], v[2:3]
	v_pk_add_f32 v[26:27], v[26:27], v[30:31]
	v_mov_b32_e32 v126, v23
	v_pk_add_f32 v[22:23], v[26:27], v[126:127]
	v_mov_b32_e32 v26, v10
	v_mov_b32_e32 v27, v128
	v_pk_add_f32 v[22:23], v[22:23], v[26:27]
	v_mov_b32_e32 v128, v11
	v_pk_add_f32 v[10:11], v[22:23], v[128:129]
	ds_bpermute_b32 v23, v141, v11
	ds_bpermute_b32 v22, v141, v10
	ds_bpermute_b32 v125, v111, v115
	ds_bpermute_b32 v124, v111, v114
	v_mov_b64_e32 v[30:31], s[48:49]
	s_waitcnt lgkmcnt(2)
	v_pk_add_f32 v[10:11], v[10:11], v[22:23]
	ds_bpermute_b32 v23, v112, v11
	ds_bpermute_b32 v22, v112, v10
	s_waitcnt lgkmcnt(2)
	v_pk_add_f32 v[26:27], v[114:115], v[124:125]
	s_waitcnt lgkmcnt(0)
	v_pk_add_f32 v[10:11], v[10:11], v[22:23]
	ds_bpermute_b32 v23, v130, v11
	ds_bpermute_b32 v22, v130, v10
	v_pk_fma_f32 v[26:27], v[26:27], s[46:47], v[30:31] op_sel_hi:[1,0,0]
	s_waitcnt lgkmcnt(0)
; DI float b2f(unsigned b) { return __uint_as_float(b << 16); }
; DI float fexp(float x) { return __builtin_amdgcn_exp2f(x * LOG2E); }
; DI void gla_g3_block(const P& p, int cgi, int hh, char* smem) {
;     ...
;       for (int r = 0; r < 4; ++r) graw[j][r] = og[(long)(t0 + 16 * slab + 4 * q4 + r) * 512 + hh * 128 + 16 * j + r16];
;     ...
;         float g = b2f(graw[j][r]);
;         float val = o[j][r] * ss[r] * gw * (g / (1.f + fexp(-g)));
;         mixin[(long)tok * 1024 + hh * 128 + v] = f2b(val);
	v_pk_add_f32 v[10:11], v[10:11], v[22:23]
	v_mul_f32_e32 v58, 0x4b800000, v27
	v_cmp_gt_f32_e32 vcc, s55, v27
	ds_bpermute_b32 v23, v111, v11
	ds_bpermute_b32 v22, v111, v10
	v_cndmask_b32_e32 v27, v27, v58, vcc
	v_rsq_f32_e32 v27, v27
	v_mul_f32_e32 v58, 0x4b800000, v26
	v_cmp_gt_f32_e64 s[4:5], s55, v26
	s_waitcnt lgkmcnt(0)
	v_pk_add_f32 v[10:11], v[10:11], v[22:23]
	v_cndmask_b32_e64 v26, v26, v58, s[4:5]
	v_mul_f32_e32 v58, 0x45800000, v27
	v_pk_fma_f32 v[10:11], v[10:11], s[46:47], v[30:31] op_sel_hi:[1,0,0]
	v_cndmask_b32_e32 v112, v27, v58, vcc
	v_mul_f32_e32 v22, 0x4b800000, v11
	v_cmp_gt_f32_e32 vcc, s55, v11
	v_cmp_gt_f32_e64 s[6:7], s55, v10
	v_rsq_f32_e32 v26, v26
	v_cndmask_b32_e32 v11, v11, v22, vcc
	v_mul_f32_e32 v22, 0x4b800000, v10
	v_rsq_f32_e32 v11, v11
	v_cndmask_b32_e64 v10, v10, v22, s[6:7]
	v_rsq_f32_e32 v10, v10
	v_mul_f32_e32 v27, 0x45800000, v26
	v_mul_f32_e32 v22, 0x45800000, v11
	v_cndmask_b32_e32 v61, v11, v22, vcc
	v_mul_f32_e32 v11, 0x45800000, v10
	v_cndmask_b32_e64 v60, v10, v11, s[6:7]
	s_waitcnt vmcnt(0)
	v_lshlrev_b32_e32 v110, 16, v173
	v_lshlrev_b32_e32 v106, 16, v174
	v_lshlrev_b32_e32 v102, 16, v175
	v_lshlrev_b32_e32 v98, 16, v176
	v_lshlrev_b32_e32 v94, 16, v177
	v_lshlrev_b32_e32 v90, 16, v178
	v_lshlrev_b32_e32 v84, 16, v179
	v_lshlrev_b32_e32 v82, 16, v180
	v_lshlrev_b32_e32 v109, 16, v181
	v_lshlrev_b32_e32 v107, 16, v182
	v_lshlrev_b32_e32 v108, 16, v183
	v_lshlrev_b32_e32 v105, 16, v184
	v_lshlrev_b32_e32 v103, 16, v185
	v_lshlrev_b32_e32 v104, 16, v186
	v_lshlrev_b32_e32 v101, 16, v187
	v_lshlrev_b32_e32 v99, 16, v188
	v_lshlrev_b32_e32 v100, 16, v189
	v_lshlrev_b32_e32 v97, 16, v190
	v_lshlrev_b32_e32 v95, 16, v191
	v_lshlrev_b32_e32 v96, 16, v192
	v_lshlrev_b32_e32 v93, 16, v193
	v_lshlrev_b32_e32 v91, 16, v194
	v_lshlrev_b32_e32 v92, 16, v195
	v_lshlrev_b32_e32 v89, 16, v196
	v_lshlrev_b32_e32 v87, 16, v197
	v_lshlrev_b32_e32 v88, 16, v198
	v_lshlrev_b32_e32 v83, 16, v199
	v_lshlrev_b32_e32 v86, 16, v228
	v_lshlrev_b32_e32 v85, 16, v229
	v_lshlrev_b32_e32 v81, 16, v230
	v_lshlrev_b32_e32 v80, 16, v231
	v_lshlrev_b32_e32 v34, 16, v232
	v_mul_f32_e32 v10, 0xbfb8aa3b, v110
	v_exp_f32_e32 v23, v10
	v_cndmask_b32_e64 v111, v26, v27, s[4:5]
	v_mul_f32_e32 v30, v56, v112
	s_waitcnt vmcnt(0)
	v_mul_f32_e32 v30, v30, v113
	v_add_f32_e32 v23, 1.0, v23
	v_div_scale_f32 v27, s[4:5], v23, v23, v110
	v_rcp_f32_e32 v26, v27
	v_or_b32_e32 v22, s50, v140
	v_and_b32_e32 v156, 48, v140
	v_bfe_u32 v157, v140, 2, 2
	v_and_b32_e32 v158, 15, v79
	v_mul_u32_u24_e32 v159, 0x210, v156
	v_add_u32_e32 v159, 16, v159
	v_mul_u32_u24_e32 v160, 0x440, v157
	v_lshl_add_u32 v200, v158, 1, v159
	v_add_u32_e32 v200, v200, v160
	v_mul_u32_u24_e32 v160, 0x110, v157
	v_lshl_add_u32 v201, v158, 4, v159
	v_add_u32_e32 v201, v201, v160
	v_add3_u32 v161, s50, v156, v157
	v_mov_b32_e32 v163, 0
	v_lshlrev_b32_e32 v162, 11, v161
	v_mul_u32_u24_e32 v164, 14, v158
	v_lshl_add_u64 v[202:203], v[46:47], 0, s[44:45]
	v_add_u32_e32 v162, v162, v164
	v_lshl_add_u64 v[202:203], v[202:203], 0, v[162:163]
	v_mov_b32_e32 v56, v166
	v_mov_b32_e32 v114, v167
	v_mov_b32_e32 v115, v168
	v_mov_b32_e32 v116, v169
	v_mov_b32_e32 v118, v170
	v_mov_b32_e32 v119, v171
	v_mov_b32_e32 v117, v172
	v_lshl_add_u64 v[10:11], v[46:47], 0, s[44:45]
	v_fma_f32 v31, -v27, v26, 1.0
	v_fmac_f32_e32 v26, v31, v26
	v_div_scale_f32 v31, vcc, v110, v23, v110
	v_mul_f32_e32 v58, v31, v26
	v_fma_f32 v59, -v27, v58, v31
	v_fmac_f32_e32 v58, v59, v26
	v_fma_f32 v27, -v27, v58, v31
	v_div_fmas_f32 v26, v27, v26, v58
	v_div_fixup_f32 v23, v26, v23, v110
	v_mul_f32_e32 v26, 0xbfb8aa3b, v109
	v_exp_f32_e32 v31, v26
	v_mul_f32_e32 v23, v23, v30
	v_cvt_pk_bf16_f32 v30, v23, s0
	v_ashrrev_i32_e32 v23, 31, v22
	v_lshlrev_b64 v[26:27], 11, v[22:23]
	v_add_f32_e32 v23, 1.0, v31
	v_lshl_add_u64 v[58:59], v[10:11], 0, v[26:27]
	v_div_scale_f32 v27, s[4:5], v23, v23, v109
	ds_write_b16 v200, v30 offset:0
	v_rcp_f32_e32 v30, v27
	v_mul_f32_e32 v31, v57, v111
	v_or_b32_e32 v26, 1, v22
	v_mul_f32_e32 v31, v113, v31
	v_fma_f32 v57, -v27, v30, 1.0
	v_fmac_f32_e32 v30, v57, v30
	v_div_scale_f32 v57, vcc, v109, v23, v109
	v_mul_f32_e32 v110, v57, v30
	v_fma_f32 v120, -v27, v110, v57
	v_fmac_f32_e32 v110, v120, v30
	v_fma_f32 v27, -v27, v110, v57
	v_div_fmas_f32 v27, v27, v30, v110
	v_mul_f32_e32 v30, 0xbfb8aa3b, v108
	v_exp_f32_e32 v57, v30
	v_div_fixup_f32 v23, v27, v23, v109
	v_ashrrev_i32_e32 v27, 31, v26
	v_mul_f32_e32 v23, v23, v31
	v_lshlrev_b64 v[26:27], 11, v[26:27]
	v_cvt_pk_bf16_f32 v23, v23, s0
	v_lshl_add_u64 v[30:31], v[10:11], 0, v[26:27]
	ds_write_b16 v200, v23 offset:272
	v_add_f32_e32 v23, 1.0, v57
	v_div_scale_f32 v27, s[4:5], v23, v23, v108
	v_rcp_f32_e32 v57, v27
	v_mul_f32_e32 v18, v18, v61
	v_mul_f32_e32 v18, v113, v18
	v_or_b32_e32 v26, 2, v22
	v_fma_f32 v109, -v27, v57, 1.0
	v_fmac_f32_e32 v57, v109, v57
	v_div_scale_f32 v109, vcc, v108, v23, v108
	v_mul_f32_e32 v110, v109, v57
	v_fma_f32 v120, -v27, v110, v109
	v_fmac_f32_e32 v110, v120, v57
	v_fma_f32 v27, -v27, v110, v109
	v_div_fmas_f32 v27, v27, v57, v110
	v_div_fixup_f32 v23, v27, v23, v108
	v_mul_f32_e32 v18, v23, v18
	v_mul_f32_e32 v23, 0xbfb8aa3b, v107
	v_exp_f32_e32 v23, v23
	v_ashrrev_i32_e32 v27, 31, v26
	v_lshlrev_b64 v[26:27], 11, v[26:27]
	v_cvt_pk_bf16_f32 v18, v18, s0
	v_add_f32_e32 v23, 1.0, v23
	v_div_scale_f32 v57, s[4:5], v23, v23, v107
	v_rcp_f32_e32 v108, v57
	v_lshl_add_u64 v[26:27], v[10:11], 0, v[26:27]
	ds_write_b16 v200, v18 offset:544
	v_or_b32_e32 v18, 3, v22
	v_fma_f32 v22, -v57, v108, 1.0
	v_fmac_f32_e32 v108, v22, v108
	v_div_scale_f32 v22, vcc, v107, v23, v107
	v_mul_f32_e32 v109, v22, v108
	v_fma_f32 v110, -v57, v109, v22
	v_fmac_f32_e32 v109, v110, v108
	v_fma_f32 v22, -v57, v109, v22
	v_mul_f32_e32 v19, v19, v60
	v_div_fmas_f32 v22, v22, v108, v109
	v_mul_f32_e32 v19, v113, v19
	v_div_fixup_f32 v22, v22, v23, v107
	v_mul_f32_e32 v19, v22, v19
	v_cvt_pk_bf16_f32 v22, v19, s0
	v_mul_f32_e32 v19, 0xbfb8aa3b, v106
	v_exp_f32_e32 v23, v19
	v_ashrrev_i32_e32 v19, 31, v18
	v_lshlrev_b64 v[18:19], 11, v[18:19]
	v_lshl_add_u64 v[10:11], v[10:11], 0, v[18:19]
	v_add_f32_e32 v18, 1.0, v23
	v_div_scale_f32 v19, s[4:5], v18, v18, v106
	v_rcp_f32_e32 v23, v19
	ds_write_b16 v200, v22 offset:816
	v_mul_f32_e32 v22, v28, v112
	s_waitcnt vmcnt(0)
; DI float b2f(unsigned b) { return __uint_as_float(b << 16); }
; DI float fexp(float x) { return __builtin_amdgcn_exp2f(x * LOG2E); }
; DI void gla_g3_block(const P& p, int cgi, int hh, char* smem) {
;     ...
;     for (int j = 0; j < 8; ++j) {
;       const int v = 16 * j + r16;
;       const float gw = p.gla_norm_w[v];
; #pragma unroll
;       for (int r = 0; r < 4; ++r) {
;         const int tok = t0 + 16 * slab + 4 * q4 + r;
;         float g = b2f(graw[j][r]);
;         float val = o[j][r] * ss[r] * gw * (g / (1.f + fexp(-g)));
;         mixin[(long)tok * 1024 + hh * 128 + v] = f2b(val);
	v_mul_f32_e32 v22, v22, v56
	v_fma_f32 v28, -v19, v23, 1.0
	v_fmac_f32_e32 v23, v28, v23
	v_div_scale_f32 v28, vcc, v106, v18, v106
	v_mul_f32_e32 v57, v28, v23
	v_fma_f32 v107, -v19, v57, v28
	v_fmac_f32_e32 v57, v107, v23
	v_fma_f32 v19, -v19, v57, v28
	v_div_fmas_f32 v19, v19, v23, v57
	v_mul_f32_e32 v23, 0xbfb8aa3b, v105
	v_exp_f32_e32 v23, v23
	v_div_fixup_f32 v18, v19, v18, v106
	v_mul_f32_e32 v18, v18, v22
	v_cvt_pk_bf16_f32 v18, v18, s0
	v_add_f32_e32 v19, 1.0, v23
	v_div_scale_f32 v22, s[4:5], v19, v19, v105
	v_rcp_f32_e32 v23, v22
	ds_write_b16 v200, v18 offset:32
	v_mul_f32_e32 v18, v29, v111
	v_mul_f32_e32 v18, v18, v56
	v_fma_f32 v28, -v22, v23, 1.0
	v_fmac_f32_e32 v23, v28, v23
	v_div_scale_f32 v28, vcc, v105, v19, v105
	v_mul_f32_e32 v29, v28, v23
	v_fma_f32 v57, -v22, v29, v28
	v_fmac_f32_e32 v29, v57, v23
	v_fma_f32 v22, -v22, v29, v28
	v_div_fmas_f32 v22, v22, v23, v29
	v_mul_f32_e32 v23, 0xbfb8aa3b, v104
	v_exp_f32_e32 v23, v23
	v_div_fixup_f32 v19, v22, v19, v105
	v_mul_f32_e32 v18, v19, v18
	v_cvt_pk_bf16_f32 v18, v18, s0
	v_add_f32_e32 v19, 1.0, v23
	v_div_scale_f32 v22, s[4:5], v19, v19, v104
	v_rcp_f32_e32 v23, v22
	ds_write_b16 v200, v18 offset:304
	v_mul_f32_e32 v14, v14, v61
	v_mul_f32_e32 v14, v14, v56
	v_fma_f32 v18, -v22, v23, 1.0
	v_fmac_f32_e32 v23, v18, v23
	v_div_scale_f32 v18, vcc, v104, v19, v104
	v_mul_f32_e32 v28, v18, v23
	v_fma_f32 v29, -v22, v28, v18
	v_fmac_f32_e32 v28, v29, v23
	v_fma_f32 v18, -v22, v28, v18
	v_mul_f32_e32 v22, 0xbfb8aa3b, v103
	v_exp_f32_e32 v22, v22
	v_div_fmas_f32 v18, v18, v23, v28
	v_div_fixup_f32 v18, v18, v19, v104
	v_mul_f32_e32 v14, v18, v14
	v_add_f32_e32 v18, 1.0, v22
	v_div_scale_f32 v19, s[4:5], v18, v18, v103
	v_rcp_f32_e32 v22, v19
	v_cvt_pk_bf16_f32 v14, v14, s0
	ds_write_b16 v200, v14 offset:576
	v_mul_f32_e32 v14, v15, v60
	v_fma_f32 v15, -v19, v22, 1.0
	v_fmac_f32_e32 v22, v15, v22
	v_div_scale_f32 v15, vcc, v103, v18, v103
	v_mul_f32_e32 v23, v15, v22
	v_fma_f32 v28, -v19, v23, v15
	v_fmac_f32_e32 v23, v28, v22
	v_fma_f32 v15, -v19, v23, v15
	v_mul_f32_e32 v19, 0xbfb8aa3b, v102
	v_exp_f32_e32 v19, v19
	v_div_fmas_f32 v15, v15, v22, v23
	v_mul_f32_e32 v14, v56, v14
	v_div_fixup_f32 v15, v15, v18, v103
	v_mul_f32_e32 v14, v15, v14
	v_add_f32_e32 v15, 1.0, v19
	v_div_scale_f32 v18, s[4:5], v15, v15, v102
	v_rcp_f32_e32 v19, v18
	v_cvt_pk_bf16_f32 v14, v14, s0
	ds_write_b16 v200, v14 offset:848
	v_mul_f32_e32 v14, v54, v112
	v_fma_f32 v22, -v18, v19, 1.0
	v_fmac_f32_e32 v19, v22, v19
	v_div_scale_f32 v22, vcc, v102, v15, v102
	v_mul_f32_e32 v23, v22, v19
	v_fma_f32 v28, -v18, v23, v22
	v_fmac_f32_e32 v23, v28, v19
	v_fma_f32 v18, -v18, v23, v22
	v_div_fmas_f32 v18, v18, v19, v23
	v_mul_f32_e32 v19, 0xbfb8aa3b, v101
	v_exp_f32_e32 v19, v19
	s_waitcnt vmcnt(0)
	v_mul_f32_e32 v14, v14, v114
	v_div_fixup_f32 v15, v18, v15, v102
	v_mul_f32_e32 v14, v15, v14
	v_add_f32_e32 v15, 1.0, v19
	v_div_scale_f32 v18, s[4:5], v15, v15, v101
	v_rcp_f32_e32 v19, v18
	v_cvt_pk_bf16_f32 v14, v14, s0
	ds_write_b16 v200, v14 offset:64
	v_mul_f32_e32 v14, v24, v111
	v_fma_f32 v22, -v18, v19, 1.0
	v_fmac_f32_e32 v19, v22, v19
	v_div_scale_f32 v22, vcc, v101, v15, v101
	v_mul_f32_e32 v23, v22, v19
	v_fma_f32 v24, -v18, v23, v22
	v_fmac_f32_e32 v23, v24, v19
	v_fma_f32 v18, -v18, v23, v22
	v_div_fmas_f32 v18, v18, v19, v23
	v_mul_f32_e32 v19, 0xbfb8aa3b, v100
	v_exp_f32_e32 v19, v19
	v_mul_f32_e32 v14, v14, v114
	v_div_fixup_f32 v15, v18, v15, v101
	v_mul_f32_e32 v14, v15, v14
	v_add_f32_e32 v15, 1.0, v19
	v_div_scale_f32 v18, s[4:5], v15, v15, v100
	v_rcp_f32_e32 v19, v18
	v_cvt_pk_bf16_f32 v14, v14, s0
	ds_write_b16 v200, v14 offset:336
	v_mul_f32_e32 v14, v16, v61
	v_fma_f32 v16, -v18, v19, 1.0
	v_fmac_f32_e32 v19, v16, v19
	v_div_scale_f32 v16, vcc, v100, v15, v100
	v_mul_f32_e32 v22, v16, v19
	v_fma_f32 v23, -v18, v22, v16
	v_fmac_f32_e32 v22, v23, v19
	v_fma_f32 v16, -v18, v22, v16
	v_mul_f32_e32 v18, 0xbfb8aa3b, v99
	v_exp_f32_e32 v18, v18
	v_div_fmas_f32 v16, v16, v19, v22
	v_mul_f32_e32 v14, v14, v114
	v_div_fixup_f32 v15, v16, v15, v100
	v_mul_f32_e32 v14, v15, v14
	v_add_f32_e32 v15, 1.0, v18
	v_div_scale_f32 v16, s[4:5], v15, v15, v99
	v_rcp_f32_e32 v18, v16
	v_cvt_pk_bf16_f32 v14, v14, s0
	ds_write_b16 v200, v14 offset:608
	v_mul_f32_e32 v14, v20, v60
	v_fma_f32 v19, -v16, v18, 1.0
	v_fmac_f32_e32 v18, v19, v18
	v_div_scale_f32 v19, vcc, v99, v15, v99
	v_mul_f32_e32 v20, v19, v18
	v_fma_f32 v22, -v16, v20, v19
	v_fmac_f32_e32 v20, v22, v18
	v_fma_f32 v16, -v16, v20, v19
	v_div_fmas_f32 v16, v16, v18, v20
	v_mul_f32_e32 v18, 0xbfb8aa3b, v98
	v_exp_f32_e32 v18, v18
	v_mul_f32_e32 v14, v14, v114
	v_div_fixup_f32 v15, v16, v15, v99
	v_mul_f32_e32 v14, v15, v14
	v_add_f32_e32 v15, 1.0, v18
	v_div_scale_f32 v16, s[4:5], v15, v15, v98
	v_rcp_f32_e32 v18, v16
	v_cvt_pk_bf16_f32 v14, v14, s0
	ds_write_b16 v200, v14 offset:880
	v_mul_f32_e32 v14, v55, v112
	v_fma_f32 v19, -v16, v18, 1.0
	v_fmac_f32_e32 v18, v19, v18
	v_div_scale_f32 v19, vcc, v98, v15, v98
	v_mul_f32_e32 v20, v19, v18
	v_fma_f32 v22, -v16, v20, v19
	v_fmac_f32_e32 v20, v22, v18
	v_fma_f32 v16, -v16, v20, v19
	v_div_fmas_f32 v16, v16, v18, v20
	v_mul_f32_e32 v18, 0xbfb8aa3b, v97
	v_exp_f32_e32 v18, v18
	s_waitcnt vmcnt(0)
; DI float b2f(unsigned b) { return __uint_as_float(b << 16); }
; DI float fexp(float x) { return __builtin_amdgcn_exp2f(x * LOG2E); }
; DI void gla_g3_block(const P& p, int cgi, int hh, char* smem) {
;     ...
;     for (int j = 0; j < 8; ++j) {
;       const int v = 16 * j + r16;
;       const float gw = p.gla_norm_w[v];
; #pragma unroll
;       for (int r = 0; r < 4; ++r) {
;         const int tok = t0 + 16 * slab + 4 * q4 + r;
;         float g = b2f(graw[j][r]);
;         float val = o[j][r] * ss[r] * gw * (g / (1.f + fexp(-g)));
;         mixin[(long)tok * 1024 + hh * 128 + v] = f2b(val);
	v_mul_f32_e32 v14, v14, v115
	v_div_fixup_f32 v15, v16, v15, v98
	v_mul_f32_e32 v14, v15, v14
	v_add_f32_e32 v15, 1.0, v18
	v_div_scale_f32 v16, s[4:5], v15, v15, v97
	v_rcp_f32_e32 v18, v16
	v_cvt_pk_bf16_f32 v14, v14, s0
	ds_write_b16 v200, v14 offset:96
	v_mul_f32_e32 v14, v25, v111
	v_fma_f32 v19, -v16, v18, 1.0
	v_fmac_f32_e32 v18, v19, v18
	v_div_scale_f32 v19, vcc, v97, v15, v97
	v_mul_f32_e32 v20, v19, v18
	v_fma_f32 v22, -v16, v20, v19
	v_fmac_f32_e32 v20, v22, v18
	v_fma_f32 v16, -v16, v20, v19
	v_div_fmas_f32 v16, v16, v18, v20
	v_mul_f32_e32 v18, 0xbfb8aa3b, v96
	v_exp_f32_e32 v18, v18
	v_mul_f32_e32 v14, v14, v115
	v_div_fixup_f32 v15, v16, v15, v97
	v_mul_f32_e32 v14, v15, v14
	v_add_f32_e32 v15, 1.0, v18
	v_div_scale_f32 v16, s[4:5], v15, v15, v96
	v_rcp_f32_e32 v18, v16
	v_cvt_pk_bf16_f32 v14, v14, s0
	ds_write_b16 v200, v14 offset:368
	v_mul_f32_e32 v14, v17, v61
	v_fma_f32 v17, -v16, v18, 1.0
	v_fmac_f32_e32 v18, v17, v18
	v_div_scale_f32 v17, vcc, v96, v15, v96
	v_mul_f32_e32 v19, v17, v18
	v_fma_f32 v20, -v16, v19, v17
	v_fmac_f32_e32 v19, v20, v18
	v_fma_f32 v16, -v16, v19, v17
	v_mul_f32_e32 v17, 0xbfb8aa3b, v95
	v_exp_f32_e32 v17, v17
	v_div_fmas_f32 v16, v16, v18, v19
	v_mul_f32_e32 v14, v14, v115
	v_div_fixup_f32 v15, v16, v15, v96
	v_mul_f32_e32 v14, v15, v14
	v_add_f32_e32 v15, 1.0, v17
	v_div_scale_f32 v16, s[4:5], v15, v15, v95
	v_rcp_f32_e32 v17, v16
	v_cvt_pk_bf16_f32 v14, v14, s0
	ds_write_b16 v200, v14 offset:640
	v_mul_f32_e32 v14, v21, v60
	v_fma_f32 v18, -v16, v17, 1.0
	v_fmac_f32_e32 v17, v18, v17
	v_div_scale_f32 v18, vcc, v95, v15, v95
	v_mul_f32_e32 v19, v18, v17
	v_fma_f32 v20, -v16, v19, v18
	v_fmac_f32_e32 v19, v20, v17
	v_fma_f32 v16, -v16, v19, v18
	v_div_fmas_f32 v16, v16, v17, v19
	v_mul_f32_e32 v17, 0xbfb8aa3b, v94
	v_exp_f32_e32 v17, v17
	v_mul_f32_e32 v14, v14, v115
	v_div_fixup_f32 v15, v16, v15, v95
	v_mul_f32_e32 v14, v15, v14
	v_add_f32_e32 v15, 1.0, v17
	v_div_scale_f32 v16, s[4:5], v15, v15, v94
	v_rcp_f32_e32 v17, v16
	v_cvt_pk_bf16_f32 v14, v14, s0
	ds_write_b16 v200, v14 offset:912
	v_mul_f32_e32 v14, v52, v112
	v_fma_f32 v18, -v16, v17, 1.0
	v_fmac_f32_e32 v17, v18, v17
	v_div_scale_f32 v18, vcc, v94, v15, v94
	v_mul_f32_e32 v19, v18, v17
	v_fma_f32 v20, -v16, v19, v18
	v_fmac_f32_e32 v19, v20, v17
	v_fma_f32 v16, -v16, v19, v18
	v_div_fmas_f32 v16, v16, v17, v19
	v_mul_f32_e32 v17, 0xbfb8aa3b, v93
	v_exp_f32_e32 v17, v17
	s_waitcnt vmcnt(0)
	v_mul_f32_e32 v14, v14, v116
	v_div_fixup_f32 v15, v16, v15, v94
	v_mul_f32_e32 v14, v15, v14
	v_add_f32_e32 v15, 1.0, v17
	v_div_scale_f32 v16, s[4:5], v15, v15, v93
	v_rcp_f32_e32 v17, v16
	v_cvt_pk_bf16_f32 v14, v14, s0
	ds_write_b16 v200, v14 offset:128
	v_mul_f32_e32 v12, v12, v111
	v_fma_f32 v14, -v16, v17, 1.0
	v_fmac_f32_e32 v17, v14, v17
	v_div_scale_f32 v14, vcc, v93, v15, v93
	v_mul_f32_e32 v18, v14, v17
	v_fma_f32 v19, -v16, v18, v14
	v_fmac_f32_e32 v18, v19, v17
	v_fma_f32 v14, -v16, v18, v14
	v_mul_f32_e32 v16, 0xbfb8aa3b, v92
	v_exp_f32_e32 v16, v16
	v_div_fmas_f32 v14, v14, v17, v18
	v_mul_f32_e32 v12, v12, v116
	v_div_fixup_f32 v14, v14, v15, v93
	v_mul_f32_e32 v12, v14, v12
	v_add_f32_e32 v14, 1.0, v16
	v_div_scale_f32 v15, s[4:5], v14, v14, v92
	v_rcp_f32_e32 v16, v15
	v_cvt_pk_bf16_f32 v12, v12, s0
	ds_write_b16 v200, v12 offset:400
	v_mul_f32_e32 v8, v8, v61
	v_fma_f32 v12, -v15, v16, 1.0
	v_fmac_f32_e32 v16, v12, v16
	v_div_scale_f32 v12, vcc, v92, v14, v92
	v_mul_f32_e32 v17, v12, v16
	v_fma_f32 v18, -v15, v17, v12
	v_fmac_f32_e32 v17, v18, v16
	v_fma_f32 v12, -v15, v17, v12
	v_mul_f32_e32 v15, 0xbfb8aa3b, v91
	v_exp_f32_e32 v15, v15
	v_div_fmas_f32 v12, v12, v16, v17
	v_mul_f32_e32 v8, v8, v116
	v_div_fixup_f32 v12, v12, v14, v92
	v_mul_f32_e32 v8, v12, v8
	v_add_f32_e32 v12, 1.0, v15
	v_div_scale_f32 v14, s[4:5], v12, v12, v91
	v_rcp_f32_e32 v15, v14
	v_cvt_pk_bf16_f32 v8, v8, s0
	ds_write_b16 v200, v8 offset:672
	v_mul_f32_e32 v6, v6, v60
	v_fma_f32 v8, -v14, v15, 1.0
	v_fmac_f32_e32 v15, v8, v15
	v_div_scale_f32 v8, vcc, v91, v12, v91
	v_mul_f32_e32 v16, v8, v15
	v_fma_f32 v17, -v14, v16, v8
	v_fmac_f32_e32 v16, v17, v15
	v_fma_f32 v8, -v14, v16, v8
	v_mul_f32_e32 v14, 0xbfb8aa3b, v90
	v_exp_f32_e32 v14, v14
	v_div_fmas_f32 v8, v8, v15, v16
	v_mul_f32_e32 v6, v6, v116
	v_div_fixup_f32 v8, v8, v12, v91
	v_mul_f32_e32 v6, v8, v6
	v_add_f32_e32 v8, 1.0, v14
	v_div_scale_f32 v12, s[4:5], v8, v8, v90
	v_rcp_f32_e32 v14, v12
	v_cvt_pk_bf16_f32 v6, v6, s0
	ds_write_b16 v200, v6 offset:944
	v_mul_f32_e32 v6, v53, v112
	v_fma_f32 v15, -v12, v14, 1.0
	v_fmac_f32_e32 v14, v15, v14
	v_div_scale_f32 v15, vcc, v90, v8, v90
	v_mul_f32_e32 v16, v15, v14
	v_fma_f32 v17, -v12, v16, v15
	v_fmac_f32_e32 v16, v17, v14
	v_fma_f32 v12, -v12, v16, v15
	v_div_fmas_f32 v12, v12, v14, v16
	v_mul_f32_e32 v14, 0xbfb8aa3b, v89
	v_exp_f32_e32 v14, v14
	s_waitcnt vmcnt(0)
; DI float b2f(unsigned b) { return __uint_as_float(b << 16); }
; DI float fexp(float x) { return __builtin_amdgcn_exp2f(x * LOG2E); }
; DI void gla_g3_block(const P& p, int cgi, int hh, char* smem) {
;     ...
;     for (int j = 0; j < 8; ++j) {
;       const int v = 16 * j + r16;
;       const float gw = p.gla_norm_w[v];
; #pragma unroll
;       for (int r = 0; r < 4; ++r) {
;         const int tok = t0 + 16 * slab + 4 * q4 + r;
;         float g = b2f(graw[j][r]);
;         float val = o[j][r] * ss[r] * gw * (g / (1.f + fexp(-g)));
;         mixin[(long)tok * 1024 + hh * 128 + v] = f2b(val);
	v_mul_f32_e32 v6, v6, v118
	v_div_fixup_f32 v8, v12, v8, v90
	v_mul_f32_e32 v6, v8, v6
	v_add_f32_e32 v8, 1.0, v14
	v_div_scale_f32 v12, s[4:5], v8, v8, v89
	v_rcp_f32_e32 v14, v12
	v_cvt_pk_bf16_f32 v6, v6, s0
	ds_write_b16 v200, v6 offset:160
	v_mul_f32_e32 v6, v13, v111
	v_fma_f32 v13, -v12, v14, 1.0
	v_fmac_f32_e32 v14, v13, v14
	v_div_scale_f32 v13, vcc, v89, v8, v89
	v_mul_f32_e32 v15, v13, v14
	v_fma_f32 v16, -v12, v15, v13
	v_fmac_f32_e32 v15, v16, v14
	v_fma_f32 v12, -v12, v15, v13
	v_mul_f32_e32 v13, 0xbfb8aa3b, v88
	v_exp_f32_e32 v13, v13
	v_div_fmas_f32 v12, v12, v14, v15
	v_mul_f32_e32 v6, v6, v118
	v_div_fixup_f32 v8, v12, v8, v89
	v_mul_f32_e32 v6, v8, v6
	v_add_f32_e32 v8, 1.0, v13
	v_div_scale_f32 v12, s[4:5], v8, v8, v88
	v_rcp_f32_e32 v13, v12
	v_cvt_pk_bf16_f32 v6, v6, s0
	ds_write_b16 v200, v6 offset:432
	v_mul_f32_e32 v6, v9, v61
	v_fma_f32 v9, -v12, v13, 1.0
	v_fmac_f32_e32 v13, v9, v13
	v_div_scale_f32 v9, vcc, v88, v8, v88
	v_mul_f32_e32 v14, v9, v13
	v_fma_f32 v15, -v12, v14, v9
	v_fmac_f32_e32 v14, v15, v13
	v_fma_f32 v9, -v12, v14, v9
	v_mul_f32_e32 v12, 0xbfb8aa3b, v87
	v_exp_f32_e32 v12, v12
	v_div_fmas_f32 v9, v9, v13, v14
	v_mul_f32_e32 v6, v6, v118
	v_div_fixup_f32 v8, v9, v8, v88
	v_mul_f32_e32 v6, v8, v6
	v_add_f32_e32 v8, 1.0, v12
	v_div_scale_f32 v9, s[4:5], v8, v8, v87
	v_rcp_f32_e32 v12, v9
	v_cvt_pk_bf16_f32 v6, v6, s0
	ds_write_b16 v200, v6 offset:704
	v_mul_f32_e32 v6, v7, v60
	v_fma_f32 v7, -v9, v12, 1.0
	v_fmac_f32_e32 v12, v7, v12
	v_div_scale_f32 v7, vcc, v87, v8, v87
	v_mul_f32_e32 v13, v7, v12
	v_fma_f32 v14, -v9, v13, v7
	v_fmac_f32_e32 v13, v14, v12
	v_fma_f32 v7, -v9, v13, v7
	v_mul_f32_e32 v9, 0xbfb8aa3b, v84
	v_exp_f32_e32 v9, v9
	v_div_fmas_f32 v7, v7, v12, v13
	v_mul_f32_e32 v6, v6, v118
	v_div_fixup_f32 v7, v7, v8, v87
	v_mul_f32_e32 v6, v7, v6
	v_add_f32_e32 v7, 1.0, v9
	v_div_scale_f32 v8, s[4:5], v7, v7, v84
	v_rcp_f32_e32 v9, v8
	v_cvt_pk_bf16_f32 v6, v6, s0
	ds_write_b16 v200, v6 offset:976
	v_mul_f32_e32 v6, v50, v112
	v_fma_f32 v12, -v8, v9, 1.0
	v_fmac_f32_e32 v9, v12, v9
	v_div_scale_f32 v12, vcc, v84, v7, v84
	v_mul_f32_e32 v13, v12, v9
	v_fma_f32 v14, -v8, v13, v12
	v_fmac_f32_e32 v13, v14, v9
	v_fma_f32 v8, -v8, v13, v12
	v_div_fmas_f32 v8, v8, v9, v13
	v_mul_f32_e32 v9, 0xbfb8aa3b, v83
	v_exp_f32_e32 v9, v9
	s_waitcnt vmcnt(0)
	v_mul_f32_e32 v6, v6, v119
	v_div_fixup_f32 v7, v8, v7, v84
	v_mul_f32_e32 v6, v7, v6
	v_add_f32_e32 v7, 1.0, v9
	v_div_scale_f32 v8, s[4:5], v7, v7, v83
	v_rcp_f32_e32 v9, v8
	v_cvt_pk_bf16_f32 v6, v6, s0
	ds_write_b16 v200, v6 offset:192
	v_mul_f32_e32 v0, v0, v111
	v_fma_f32 v6, -v8, v9, 1.0
	v_fmac_f32_e32 v9, v6, v9
	v_div_scale_f32 v6, vcc, v83, v7, v83
	v_mul_f32_e32 v12, v6, v9
	v_fma_f32 v13, -v8, v12, v6
	v_fmac_f32_e32 v12, v13, v9
	v_fma_f32 v6, -v8, v12, v6
	v_mul_f32_e32 v8, 0xbfb8aa3b, v86
	v_exp_f32_e32 v8, v8
	v_div_fmas_f32 v6, v6, v9, v12
	v_mul_f32_e32 v0, v0, v119
	v_div_fixup_f32 v6, v6, v7, v83
	v_mul_f32_e32 v0, v6, v0
	v_add_f32_e32 v6, 1.0, v8
	v_div_scale_f32 v7, s[4:5], v6, v6, v86
	v_rcp_f32_e32 v8, v7
	v_cvt_pk_bf16_f32 v0, v0, s0
	ds_write_b16 v200, v0 offset:464
	v_mul_f32_e32 v0, v4, v61
	v_fma_f32 v4, -v7, v8, 1.0
	v_fmac_f32_e32 v8, v4, v8
	v_div_scale_f32 v4, vcc, v86, v6, v86
	v_mul_f32_e32 v9, v4, v8
	v_fma_f32 v12, -v7, v9, v4
	v_fmac_f32_e32 v9, v12, v8
	v_fma_f32 v4, -v7, v9, v4
	v_mul_f32_e32 v7, 0xbfb8aa3b, v85
	v_exp_f32_e32 v7, v7
	v_div_fmas_f32 v4, v4, v8, v9
	v_mul_f32_e32 v0, v0, v119
	v_div_fixup_f32 v4, v4, v6, v86
	v_mul_f32_e32 v0, v4, v0
	v_add_f32_e32 v4, 1.0, v7
	v_div_scale_f32 v6, s[4:5], v4, v4, v85
	v_rcp_f32_e32 v7, v6
	v_cvt_pk_bf16_f32 v0, v0, s0
	ds_write_b16 v200, v0 offset:736
	v_mul_f32_e32 v0, v2, v60
	v_fma_f32 v2, -v6, v7, 1.0
	v_fmac_f32_e32 v7, v2, v7
	v_div_scale_f32 v2, vcc, v85, v4, v85
	v_mul_f32_e32 v8, v2, v7
	v_fma_f32 v9, -v6, v8, v2
	v_fmac_f32_e32 v8, v9, v7
	v_fma_f32 v2, -v6, v8, v2
	v_mul_f32_e32 v6, 0xbfb8aa3b, v82
	v_exp_f32_e32 v6, v6
	v_div_fmas_f32 v2, v2, v7, v8
	v_mul_f32_e32 v0, v0, v119
	v_div_fixup_f32 v2, v2, v4, v85
	v_mul_f32_e32 v0, v2, v0
	v_add_f32_e32 v2, 1.0, v6
	v_div_scale_f32 v4, s[4:5], v2, v2, v82
	v_rcp_f32_e32 v6, v4
	v_cvt_pk_bf16_f32 v0, v0, s0
	ds_write_b16 v200, v0 offset:1008
	v_mul_f32_e32 v0, v51, v112
	v_fma_f32 v7, -v4, v6, 1.0
	v_fmac_f32_e32 v6, v7, v6
	v_div_scale_f32 v7, vcc, v82, v2, v82
	v_mul_f32_e32 v8, v7, v6
	v_fma_f32 v9, -v4, v8, v7
	v_fmac_f32_e32 v8, v9, v6
	v_fma_f32 v4, -v4, v8, v7
	v_div_fmas_f32 v4, v4, v6, v8
	v_mul_f32_e32 v6, 0xbfb8aa3b, v81
	v_exp_f32_e32 v6, v6
	s_waitcnt vmcnt(0)
; DI float b2f(unsigned b) { return __uint_as_float(b << 16); }
; DI float fexp(float x) { return __builtin_amdgcn_exp2f(x * LOG2E); }
; DI void gla_g3_block(const P& p, int cgi, int hh, char* smem) {
;     ...
;     for (int j = 0; j < 8; ++j) {
;       const int v = 16 * j + r16;
;       const float gw = p.gla_norm_w[v];
; #pragma unroll
;       for (int r = 0; r < 4; ++r) {
;         const int tok = t0 + 16 * slab + 4 * q4 + r;
;         float g = b2f(graw[j][r]);
;         float val = o[j][r] * ss[r] * gw * (g / (1.f + fexp(-g)));
;         mixin[(long)tok * 1024 + hh * 128 + v] = f2b(val);
;       }
;     }
;   }
	v_mul_f32_e32 v0, v0, v117
	v_div_fixup_f32 v2, v4, v2, v82
	v_mul_f32_e32 v0, v2, v0
	v_add_f32_e32 v2, 1.0, v6
	v_div_scale_f32 v4, s[4:5], v2, v2, v81
	v_rcp_f32_e32 v6, v4
	v_cvt_pk_bf16_f32 v0, v0, s0
	ds_write_b16 v200, v0 offset:224
	v_mul_f32_e32 v0, v1, v111
	v_fma_f32 v1, -v4, v6, 1.0
	v_fmac_f32_e32 v6, v1, v6
	v_div_scale_f32 v1, vcc, v81, v2, v81
	v_mul_f32_e32 v7, v1, v6
	v_fma_f32 v8, -v4, v7, v1
	v_fmac_f32_e32 v7, v8, v6
	v_fma_f32 v1, -v4, v7, v1
	v_mul_f32_e32 v4, 0xbfb8aa3b, v80
	v_exp_f32_e32 v4, v4
	v_div_fmas_f32 v1, v1, v6, v7
	v_mul_f32_e32 v0, v0, v117
	v_div_fixup_f32 v1, v1, v2, v81
	v_mul_f32_e32 v0, v1, v0
	v_add_f32_e32 v1, 1.0, v4
	v_div_scale_f32 v2, s[4:5], v1, v1, v80
	v_rcp_f32_e32 v4, v2
	v_cvt_pk_bf16_f32 v0, v0, s0
	ds_write_b16 v200, v0 offset:496
	v_mul_f32_e32 v0, v5, v61
	v_fma_f32 v5, -v2, v4, 1.0
	v_fmac_f32_e32 v4, v5, v4
	v_div_scale_f32 v5, vcc, v80, v1, v80
	v_mul_f32_e32 v6, v5, v4
	v_fma_f32 v7, -v2, v6, v5
	v_fmac_f32_e32 v6, v7, v4
	v_fma_f32 v2, -v2, v6, v5
	v_div_fmas_f32 v2, v2, v4, v6
	v_mul_f32_e32 v4, 0xbfb8aa3b, v34
	v_exp_f32_e32 v4, v4
	v_mul_f32_e32 v0, v0, v117
	v_div_fixup_f32 v1, v2, v1, v80
	v_mul_f32_e32 v0, v1, v0
	v_add_f32_e32 v1, 1.0, v4
	v_div_scale_f32 v2, s[4:5], v1, v1, v34
	v_rcp_f32_e32 v4, v2
	v_cvt_pk_bf16_f32 v0, v0, s0
	ds_write_b16 v200, v0 offset:768
	v_mul_f32_e32 v0, v3, v60
	v_fma_f32 v3, -v2, v4, 1.0
	v_fmac_f32_e32 v4, v3, v4
	v_div_scale_f32 v3, vcc, v34, v1, v34
	v_mul_f32_e32 v5, v3, v4
	v_fma_f32 v6, -v2, v5, v3
	v_fmac_f32_e32 v5, v6, v4
	v_fma_f32 v2, -v2, v5, v3
	v_div_fmas_f32 v2, v2, v4, v5
	v_mul_f32_e32 v0, v0, v117
	v_div_fixup_f32 v1, v2, v1, v34
	v_mul_f32_e32 v0, v1, v0
	v_cvt_pk_bf16_f32 v0, v0, s0
	ds_write_b16 v200, v0 offset:1040
	s_waitcnt lgkmcnt(0)
	ds_read_b128 v[212:215], v201
	ds_read_b128 v[216:219], v201 offset:1088
	ds_read_b128 v[220:223], v201 offset:2176
	ds_read_b128 v[224:227], v201 offset:3264
	v_add_co_u32_e32 v204, vcc, 0x2000, v202
	s_nop 1
	v_addc_co_u32_e32 v205, vcc, 0, v203, vcc
	v_add_co_u32_e32 v206, vcc, 0x4000, v202
	s_nop 1
	v_addc_co_u32_e32 v207, vcc, 0, v203, vcc
	v_add_co_u32_e32 v208, vcc, 0x6000, v202
	s_nop 1
	v_addc_co_u32_e32 v209, vcc, 0, v203, vcc
	s_waitcnt lgkmcnt(3)
	global_store_dwordx4 v[202:203], v[212:215], off
	s_waitcnt lgkmcnt(2)
	global_store_dwordx4 v[204:205], v[216:219], off
	s_waitcnt lgkmcnt(1)
	global_store_dwordx4 v[206:207], v[220:223], off
	s_waitcnt lgkmcnt(0)
	global_store_dwordx4 v[208:209], v[224:227], off
	s_branch .LBB0_568
